# hoist K-tile-1 prologue LDS-DMAs before first wait in SwiGLU+Resid GEMM preambles
# baseline (speedup 1.0000x reference)
.LBB0_479:
	s_andn2_b64 vcc, exec, s[2:3]
	s_cbranch_vccnz .LBB0_520
	s_waitcnt vmcnt(0)
	v_mov_b32_e32 v12, v156
	v_readlane_b32 s2, v242, 42
	s_nop 1
	v_add_u32_e32 v0, s2, v12
	v_readlane_b32 s2, v242, 43
	v_readlane_b32 s3, v242, 44
	s_andn2_b64 vcc, exec, s[2:3]
	v_readfirstlane_b32 s16, v0
	s_cbranch_vccnz .LBB0_520
	s_waitcnt lgkmcnt(0)
	v_lshlrev_b32_e32 v1, 4, v0
	v_add_u32_e32 v2, 0x2000, v1
	v_ashrrev_i32_e32 v3, 31, v2
	v_lshrrev_b32_e32 v3, 22, v3
	s_cmp_eq_u32 s78, 4
	v_add_u32_e32 v3, v2, v3
	s_cselect_b64 s[12:13], -1, 0
	v_ashrrev_i32_e32 v3, 10, v3
	s_and_b64 s[2:3], s[12:13], exec
	v_mul_i32_i24_e32 v4, 0x400, v3
	s_mov_b32 s2, 0x13c0000
	v_sub_u32_e32 v2, v2, v4
	s_cselect_b32 s4, s2, 0xf40000
	s_movk_i32 s2, 0xb00
	v_lshrrev_b32_e32 v4, 4, v2
	s_cselect_b32 s42, s79, s36
	s_cselect_b32 s43, s80, s37
	s_cselect_b32 s17, 0x400, s2
	s_cmp_eq_u32 s78, 1
	v_bitop3_b32 v2, v4, v2, 32 bitop3:0x6c
	s_cselect_b64 s[6:7], -1, 0
	v_ashrrev_i32_e32 v4, 31, v2
	s_and_b64 s[2:3], s[6:7], exec
	v_lshrrev_b32_e32 v4, 26, v4
	s_cselect_b32 s2, 0x700000, s4
	v_add_u32_e32 v4, v2, v4
	v_lshlrev_b32_e32 v6, 3, v3
	s_lshl_b32 s2, s2, 1
	v_ashrrev_i32_e32 v5, 6, v4
	v_and_b32_e32 v6, -16, v6
	v_lshlrev_b32_e32 v3, 5, v3
	s_add_u32 s44, s51, s2
	v_readlane_b32 s2, v241, 60
	v_add_u32_e32 v6, v5, v6
	v_and_b32_e32 v13, 32, v3
	v_and_b32_e32 v3, 0xc0, v4
	s_addc_u32 s45, s2, 0
	v_and_b32_e32 v5, 3, v5
	s_mov_b32 s2, 0xffffe0
	v_lshrrev_b32_e32 v7, 2, v6
	v_lshlrev_b32_e32 v8, 1, v6
	v_sub_u32_e32 v2, v2, v3
	v_and_or_b32 v5, v6, s2, v5
	v_and_b32_e32 v7, 4, v7
	v_and_b32_e32 v8, 24, v8
	v_ashrrev_i16_sdwa v2, v196, sext(v2) dst_sel:DWORD dst_unused:UNUSED_PAD src0_sel:DWORD src1_sel:BYTE_0
	v_or3_b32 v5, v5, v7, v8
	v_bfe_i32 v14, v2, 0, 16
	v_mul_u32_u24_e32 v5, s17, v5
	v_add_u32_e32 v2, v13, v14
	v_mul_lo_u32 v15, v6, s17
	v_add_lshl_u32 v168, v5, v2, 1
	v_add_lshl_u32 v170, v2, v15, 1
	v_bfe_i32 v2, v0, 27, 1
	v_lshrrev_b32_e32 v2, 22, v2
	v_add_u32_e32 v2, v1, v2
	v_and_b32_e32 v2, 0xfffffc00, v2
	v_sub_u32_e32 v1, v1, v2
	v_lshrrev_b32_e32 v2, 4, v1
	v_ashrrev_i32_e32 v4, 31, v0
	v_bitop3_b32 v1, v2, v1, 32 bitop3:0x6c
	v_lshrrev_b32_e32 v4, 26, v4
	v_ashrrev_i32_e32 v2, 31, v1
	v_add_u32_e32 v0, v0, v4
	v_lshrrev_b32_e32 v2, 26, v2
	v_ashrrev_i32_e32 v0, 6, v0
	v_add_u32_e32 v2, v1, v2
	v_lshlrev_b32_e32 v4, 3, v0
	v_ashrrev_i32_e32 v3, 6, v2
	v_and_b32_e32 v4, -16, v4
	v_add_u32_e32 v4, v3, v4
	v_and_b32_e32 v3, 3, v3
	v_and_or_b32 v3, v4, s2, v3
	v_readlane_b32 s2, v242, 58
	s_lshl_b32 s46, s17, 9
	v_lshlrev_b32_e32 v0, 5, v0
	v_readlane_b32 s3, v242, 59
	v_and_b32_e32 v16, 32, v0
	v_and_b32_e32 v0, 0xc0, v2
	s_mul_hi_i32 s4, s46, s2
	s_mul_i32 s5, s46, s2
	v_readlane_b32 s2, v242, 62
	s_ashr_i32 s24, s16, 6
	v_lshrrev_b32_e32 v5, 2, v4
	v_lshlrev_b32_e32 v6, 1, v4
	v_sub_u32_e32 v0, v1, v0
	v_readlane_b32 s3, v242, 63
	s_mov_b32 s34, s2
	s_ashr_i32 s25, s16, 8
	s_lshl_b32 s8, s17, 8
	s_lshl_b32 s47, s24, 10
	v_and_b32_e32 v5, 4, v5
	v_and_b32_e32 v6, 24, v6
	v_ashrrev_i16_sdwa v0, v196, sext(v0) dst_sel:DWORD dst_unused:UNUSED_PAD src0_sel:DWORD src1_sel:BYTE_0
	s_mul_i32 s3, s46, s34
	v_or3_b32 v3, v3, v5, v6
	v_bfe_i32 v17, v0, 0, 16
	s_mul_hi_i32 s2, s46, s2
	s_add_u32 s34, s44, s3
	v_mul_u32_u24_e32 v3, s17, v3
	v_add_u32_e32 v0, v16, v17
	s_addc_u32 s35, s45, s2
	s_add_i32 s48, s47, 0
	v_add_lshl_u32 v158, v3, v0, 1
	s_add_i32 m0, s48, 0x10000
	v_mov_b32_e32 v169, v159
	global_load_lds_dwordx4 v158, s[34:35]
	s_add_i32 m0, s48, 0x12000
	s_add_u32 s2, s34, s8
	global_load_lds_dwordx4 v168, s[34:35]
	s_addc_u32 s3, s35, 0
	s_add_i32 m0, s48, 0x14000
	v_mul_lo_u32 v18, v4, s17
	global_load_lds_dwordx4 v158, s[2:3]
	s_add_i32 m0, s48, 0x16000
	v_lshl_add_u64 v[4:5], s[2:3], 0, v[158:159]
	v_lshl_add_u64 v[6:7], s[2:3], 0, v[168:169]
	global_load_lds_dwordx4 v168, s[2:3]
	s_add_u32 s2, s42, s5
	s_addc_u32 s3, s43, s4
	s_add_i32 s49, s48, 0x2000
	v_add_lshl_u32 v172, v0, v18, 1
	s_mov_b32 m0, s48
	s_add_u32 s4, s2, s8
	global_load_lds_dwordx4 v172, s[2:3]
	s_mov_b32 m0, s49
	s_addc_u32 s5, s3, 0
	s_add_i32 s50, s48, 0x4000
	s_mov_b32 s87, s51
	global_load_lds_dwordx4 v170, s[2:3]
	s_mov_b32 m0, s50
	s_add_i32 s51, s48, 0x6000
	global_load_lds_dwordx4 v172, s[4:5]
	s_mov_b32 m0, s51
	v_mov_b32_e32 v173, v159
	global_load_lds_dwordx4 v170, s[4:5]
	v_mov_b32_e32 v171, v159
	s_cmp_eq_u32 s25, 1
	v_lshl_add_u64 v[0:1], s[34:35], 0, v[158:159]
	v_lshl_add_u64 v[2:3], s[34:35], 0, v[168:169]
	v_lshl_add_u64 v[8:9], s[2:3], 0, v[172:173]
	v_lshl_add_u64 v[10:11], s[2:3], 0, v[170:171]
	s_cselect_b64 s[4:5], -1, 0
	s_add_i32 m0, s48, 0x18000
	v_lshl_add_u64 v[0:1], v[0:1], 0, s[14:15]
	global_load_lds_dwordx4 v[0:1], off
	v_lshl_add_u64 v[0:1], v[2:3], 0, s[14:15]
	s_add_i32 m0, s48, 0x1a000
	s_add_i32 s60, s48, 0x8000
	global_load_lds_dwordx4 v[0:1], off
	v_lshl_add_u64 v[0:1], v[8:9], 0, s[14:15]
	s_mov_b32 m0, s60
	s_add_i32 s61, s48, 0xa000
	global_load_lds_dwordx4 v[0:1], off
	v_lshl_add_u64 v[0:1], v[10:11], 0, s[14:15]
	s_mov_b32 m0, s61
	s_nop 0
	global_load_lds_dwordx4 v[0:1], off
	s_add_i32 m0, s48, 0x1c000
	v_lshl_add_u64 v[0:1], v[4:5], 0, s[14:15]
	global_load_lds_dwordx4 v[0:1], off
	v_lshl_add_u64 v[0:1], v[6:7], 0, s[14:15]
	s_add_i32 m0, s48, 0x1e000
	s_nop 0
	global_load_lds_dwordx4 v[0:1], off
	s_cmp_lg_u32 s25, 1
	s_cbranch_scc1 .LBB0_483
	s_barrier
.LBB0_483:
	s_and_b64 s[38:39], s[12:13], exec
	s_cselect_b32 s38, 2, 3
	s_and_b64 s[6:7], s[6:7], exec
	s_mul_i32 s40, s75, 3
	s_cselect_b32 s6, 1, s38
	s_add_i32 s6, s6, s40
	s_lshl_b32 s6, s6, 17
	s_add_u32 s6, s26, s6
	s_addc_u32 s7, s27, 0
	s_waitcnt vmcnt(8)
	s_barrier
	v_bfe_u32 v199, v12, 4, 2
	v_and_b32_e32 v200, 15, v12
	v_lshlrev_b32_e32 v0, 4, v199
	v_lshlrev_b32_e32 v1, 2, v12
	v_cndmask_b32_e64 v174, 0.5, 1.0, s[12:13]
	v_lshl_or_b32 v0, v200, 6, v0
	s_lshl_b32 s12, s25, 13
	v_and_b32_e32 v1, 32, v1
	v_bitop3_b32 v2, v0, s12, v1 bitop3:0xde
	s_lshl_b32 s12, s24, 5
	s_and_b32 s79, s12, 0x60
	s_lshl_b32 s12, s79, 7
	v_bitop3_b32 v201, v0, s12, v1 bitop3:0xde
	v_add_u32_e32 v0, v18, v16
	s_lshr_b32 s64, s17, 6
	v_add_lshl_u32 v0, v0, v17, 1
	v_mov_b32_e32 v1, v159
	s_lshl_b32 s65, s25, 6
	s_waitcnt vmcnt(6)
	s_add_i32 s80, s64, -2
	v_lshl_add_u64 v[176:177], s[8:9], 0, v[0:1]
	v_add_u32_e32 v0, v15, v13
	s_cmpk_lt_u32 s16, 0x100
	v_add_lshl_u32 v0, v0, v14, 1
	v_readlane_b32 s16, v242, 58
	s_cselect_b64 s[12:13], -1, 0
	v_mov_b32_e32 v175, v174
	v_lshl_add_u64 v[178:179], s[8:9], 0, v[0:1]
	s_mov_b32 s81, 0
	v_add_u32_e32 v202, 0, v2
	v_readlane_b32 s84, v242, 57
	s_mov_b32 s85, s16
	s_barrier
	v_readlane_b32 s17, v242, 59
	s_branch .LBB0_486

.LBB0_621:
	v_ashrrev_i32_e32 v2, 31, v0
	v_lshrrev_b32_e32 v2, 26, v2
	v_lshlrev_b32_e32 v1, 4, v0
	v_add_u32_e32 v2, v0, v2
	v_bfe_i32 v0, v0, 27, 1
	v_lshrrev_b32_e32 v0, 22, v0
	v_add_u32_e32 v0, v1, v0
	v_and_b32_e32 v0, 0xfffffc00, v0
	v_sub_u32_e32 v0, v1, v0
	v_ashrrev_i32_e32 v9, 6, v2
	v_lshrrev_b32_e32 v2, 4, v0
	v_bitop3_b32 v0, v2, v0, 32 bitop3:0x6c
	v_ashrrev_i32_e32 v3, 31, v0
	v_lshrrev_b32_e32 v3, 26, v3
	v_add_u32_e32 v3, v0, v3
	v_lshlrev_b32_e32 v2, 3, v9
	v_ashrrev_i32_e32 v10, 6, v3
	v_and_b32_e32 v3, 0xc0, v3
	v_and_b32_e32 v2, -16, v2
	v_sub_u32_e32 v0, v0, v3
	v_add_u32_e32 v2, v10, v2
	v_ashrrev_i16_sdwa v0, v196, sext(v0) dst_sel:DWORD dst_unused:UNUSED_PAD src0_sel:DWORD src1_sel:BYTE_0
	v_lshlrev_b32_e32 v4, 5, v9
	v_bfe_i32 v11, v0, 0, 16
	v_lshlrev_b32_e32 v0, 1, v2
	v_lshrrev_b32_e32 v3, 2, v2
	v_and_b32_e32 v5, 3, v10
	s_mov_b32 s0, 0x1fffe0
	v_and_b32_e32 v4, 32, v4
	v_and_b32_e32 v0, 24, v0
	v_and_b32_e32 v3, 4, v3
	v_and_or_b32 v5, v2, s0, v5
	v_or3_b32 v0, v5, v3, v0
	v_add_lshl_u32 v3, v4, v11, 1
	s_nop 0
	v_add_u32_e32 v0, 0x2000, v1
	v_ashrrev_i32_e32 v1, 31, v0
	v_lshrrev_b32_e32 v1, 22, v1
	v_add_u32_e32 v1, v0, v1
	v_ashrrev_i32_e32 v12, 10, v1
	v_mul_i32_i24_e32 v1, 0x400, v12
	v_sub_u32_e32 v0, v0, v1
	v_lshrrev_b32_e32 v1, 4, v0
	v_bitop3_b32 v0, v1, v0, 32 bitop3:0x6c
	s_nop 0
	v_ashrrev_i32_e32 v2, 31, v0
	v_lshrrev_b32_e32 v2, 26, v2
	v_lshlrev_b32_e32 v1, 3, v12
	v_add_u32_e32 v2, v0, v2
	v_and_b32_e32 v1, -16, v1
	v_ashrrev_i32_e32 v13, 6, v2
	s_ashr_i32 s6, s4, 6
	s_ashr_i32 s5, s4, 8
	v_add_u32_e32 v1, v13, v1
	v_and_b32_e32 v4, 3, v13
	s_lshl_b32 s48, s6, 10
	v_and_or_b32 v4, v1, s0, v4
	s_and_b64 s[0:1], s[2:3], exec
	s_cselect_b32 s0, 0, 0x1380000
	s_add_u32 s49, s51, s0
	v_readlane_b32 s0, v241, 60
	v_and_b32_e32 v2, 0xc0, v2
	s_addc_u32 s50, s0, 0
	s_ashr_i32 s29, s28, 31
	s_ashr_i32 s17, s16, 31
	v_sub_u32_e32 v0, v0, v2
	s_lshl_b64 s[0:1], s[28:29], 19
	s_lshl_b64 s[2:3], s[16:17], 19
	v_ashrrev_i16_sdwa v0, v196, sext(v0) dst_sel:DWORD dst_unused:UNUSED_PAD src0_sel:DWORD src1_sel:BYTE_0
	s_add_u32 s40, s49, s2
	v_lshlrev_b32_e32 v3, 5, v12
	v_bfe_i32 v14, v0, 0, 16
	v_lshlrev_b32_e32 v0, 1, v1
	v_lshrrev_b32_e32 v2, 2, v1
	s_addc_u32 s41, s50, s3
	s_add_i32 s51, s48, 0
	v_and_b32_e32 v3, 32, v3
	v_and_b32_e32 v0, 24, v0
	v_and_b32_e32 v2, 4, v2
	s_lshr_b32 s86, s4, 6
	s_and_b32 s87, s86, 1
	s_lshl_b32 s87, s87, 2
	v_lshrrev_b32_e32 v243, 4, v8
	v_or_b32_e32 v243, s87, v243
	v_and_b32_e32 v244, 7, v8
	v_xor_b32_e32 v243, v244, v243
	v_lshlrev_b32_e32 v243, 4, v243
	v_lshrrev_b32_e32 v244, 3, v8
	s_lshl_b32 s86, s86, 3
	v_add_u32_e32 v244, s86, v244
	v_lshl_add_u32 v132, v244, 11, v243
	v_add_u32_e32 v136, 0x20000, v132
	v_and_b32_e32 v245, 31, v244
	v_bfe_u32 v246, v245, 2, 2
	v_lshlrev_b32_e32 v246, 3, v246
	v_bfe_u32 v247, v245, 4, 1
	v_lshl_or_b32 v246, v247, 2, v246
	v_and_b32_e32 v247, 3, v245
	v_or_b32_e32 v246, v246, v247
	v_and_b32_e32 v247, 0xffffffe0, v244
	v_or_b32_e32 v246, v247, v246
	v_lshl_add_u32 v134, v246, 11, v243
	v_add_u32_e32 v138, 0x20000, v134
	v_and_b32_e32 v245, 15, v8
	v_lshrrev_b32_e32 v246, 4, v8
	v_lshrrev_b32_e32 v247, 1, v245
	v_xor_b32_e32 v246, v246, v247
	v_lshlrev_b32_e32 v246, 4, v246
	v_lshl_or_b32 v246, v245, 7, v246
	s_lshr_b32 s86, s4, 8
	s_lshl_b32 s86, s86, 13
	v_or_b32_e32 v173, s86, v246
	v_xor_b32_e32 v244, 64, v173
	s_lshr_b32 s86, s4, 6
	s_and_b32 s86, s86, 3
	s_lshl_b32 s86, s86, 12
	v_or_b32_e32 v172, s86, v246
	v_xor_b32_e32 v243, 64, v172
	s_add_i32 m0, s51, 0x10000
	v_or3_b32 v0, v4, v2, v0
	v_add_lshl_u32 v2, v3, v14, 1
	global_load_lds_dwordx4 v134, s[40:41]
	s_add_i32 m0, s51, 0x12000
	s_nop 0
	s_add_u32 s2, s40, 0x40000
	global_load_lds_dwordx4 v138, s[40:41]
	s_addc_u32 s3, s41, 0
	s_add_i32 m0, s51, 0x14000
	s_nop 0
	global_load_lds_dwordx4 v134, s[2:3]
	s_add_i32 m0, s51, 0x16000
	s_add_u32 s34, s30, s0
	s_addc_u32 s35, s31, s1
	s_add_i32 s60, s51, 0x2000
	global_load_lds_dwordx4 v138, s[2:3]
	s_mov_b32 m0, s51
	s_add_u32 s0, s34, 0x40000
	global_load_lds_dwordx4 v132, s[34:35]
	s_mov_b32 m0, s60
	s_addc_u32 s1, s35, 0
	s_add_i32 s61, s51, 0x4000
	global_load_lds_dwordx4 v136, s[34:35]
	s_mov_b32 m0, s61
	s_add_i32 s64, s51, 0x6000
	global_load_lds_dwordx4 v132, s[0:1]
	s_mov_b32 m0, s64
	v_mov_b32_e32 v135, v159
	global_load_lds_dwordx4 v136, s[0:1]
	v_mov_b32_e32 v139, v159
	v_mov_b32_e32 v133, v159
	v_mov_b32_e32 v137, v159
	s_cmp_eq_u32 s5, 1
	v_lshl_add_u64 v[6:7], s[40:41], 0, v[134:135]
	v_lshl_add_u64 v[4:5], s[40:41], 0, v[138:139]
	v_lshl_add_u64 v[0:1], s[34:35], 0, v[132:133]
	s_cselect_b64 s[0:1], -1, 0
	v_lshl_add_u64 v[2:3], s[34:35], 0, v[136:137]
	s_add_i32 m0, s51, 0x18000
	v_lshl_add_u64 v[6:7], v[6:7], 0, s[14:15]
	global_load_lds_dwordx4 v[6:7], off
	v_lshl_add_u64 v[4:5], v[4:5], 0, s[14:15]
	s_add_i32 m0, s51, 0x1a000
	s_add_i32 s76, s51, 0x8000
	s_add_i32 s77, s51, 0xa000
	global_load_lds_dwordx4 v[4:5], off
	v_lshl_add_u64 v[0:1], v[0:1], 0, s[14:15]
	s_mov_b32 m0, s76
	s_add_u32 s2, s40, 0x40080
	global_load_lds_dwordx4 v[0:1], off
	v_lshl_add_u64 v[0:1], v[2:3], 0, s[14:15]
	s_mov_b32 m0, s77
	s_addc_u32 s3, s41, 0
	global_load_lds_dwordx4 v[0:1], off
	s_add_i32 m0, s51, 0x1c000
	v_lshl_add_u64 v[0:1], s[2:3], 0, v[134:135]
	global_load_lds_dwordx4 v[0:1], off
	v_lshl_add_u64 v[0:1], s[2:3], 0, v[138:139]
	s_add_i32 m0, s51, 0x1e000
	s_nop 0
	global_load_lds_dwordx4 v[0:1], off
	s_cmp_lg_u32 s5, 1
	s_cbranch_scc1 .LBB0_623
	s_barrier
.LBB0_623:
	s_lshl_b32 s2, s6, 5
	s_and_b32 s75, s2, 0x60
	s_lshl_b32 s65, s5, 6
	s_lshl_b32 s5, s5, 13
	s_lshl_b32 s6, s75, 7
	s_waitcnt vmcnt(8)
	s_barrier
	v_bfe_u32 v171, v8, 4, 2
	v_and_b32_e32 v170, 15, v8
	v_lshlrev_b32_e32 v0, 4, v171
	v_lshlrev_b32_e32 v1, 2, v8
	v_lshl_or_b32 v0, v170, 6, v0
	v_and_b32_e32 v1, 32, v1
	v_bitop3_b32 v2, v0, s5, v1 bitop3:0xde
	s_nop 0
	v_lshlrev_b32_e32 v0, 14, v9
	v_and_b32_e32 v0, 0xffff8000, v0
	v_lshl_add_u32 v0, v10, 11, v0
	v_and_b32_e32 v1, 1, v9
	v_lshl_or_b32 v0, v1, 6, v0
	v_lshl_add_u32 v140, v11, 1, v0
	v_lshlrev_b32_e32 v0, 14, v12
	v_and_b32_e32 v0, 0xffff8000, v0
	s_waitcnt vmcnt(6)
	v_lshl_add_u32 v0, v13, 11, v0
	v_and_b32_e32 v1, 1, v12
	s_cmpk_lt_u32 s4, 0x100
	v_lshl_or_b32 v0, v1, 6, v0
	s_cselect_b64 s[2:3], -1, 0
	s_or_b32 s79, s75, 0xffffea00
	v_mov_b32_e32 v141, v159
	v_lshl_add_u32 v142, v14, 1, v0
	v_mov_b32_e32 v143, v159
	s_mov_b32 s17, 0
	s_nop 0
	s_mov_b32 s80, 0
	s_barrier
	s_branch .LBB0_626
